# residual epilogues: x loads issued one row group ahead with counted vmcnt, gate loads issued with them; one-time barrier census loads batched
# speedup vs baseline: 1.0424x; 1.0089x over previous
.LBB0_143:
	v_readlane_b32 s6, v252, 11
	v_readlane_b32 s7, v252, 12
	s_mov_b64 s[8:9], -1
	s_waitcnt lgkmcnt(0)
	s_nop 2
	global_load_dword v0, v145, s[6:7] sc1
	v_readlane_b32 s6, v252, 13
	v_readlane_b32 s7, v252, 14
	s_nop 4
	global_load_dword v1, v145, s[6:7] sc1
	v_readlane_b32 s6, v252, 15
	v_readlane_b32 s7, v252, 16
	s_nop 1
	s_nop 2
	global_load_dword v2, v145, s[6:7] sc1
	v_readlane_b32 s6, v252, 17
	v_readlane_b32 s7, v252, 18
	s_nop 1
	s_nop 2
	global_load_dword v3, v145, s[6:7] sc1
	v_readlane_b32 s6, v252, 19
	v_readlane_b32 s7, v252, 20
	s_nop 1
	s_nop 2
	global_load_dword v4, v145, s[6:7] sc1
	v_readlane_b32 s6, v252, 21
	v_readlane_b32 s7, v252, 22
	s_nop 1
	s_nop 2
	global_load_dword v5, v145, s[6:7] sc1
	v_readlane_b32 s6, v252, 23
	v_readlane_b32 s7, v252, 24
	s_nop 1
	s_nop 2
	global_load_dword v6, v145, s[6:7] sc1
	v_readlane_b32 s6, v252, 25
	v_readlane_b32 s7, v252, 26
	s_nop 1
	s_nop 2
	global_load_dword v7, v145, s[6:7] sc1
	v_readlane_b32 s6, v252, 27
	v_readlane_b32 s7, v252, 28
	s_nop 1
	s_nop 2
	global_load_dword v8, v145, s[6:7] sc1
	v_readlane_b32 s6, v252, 29
	v_readlane_b32 s7, v252, 30
	s_nop 1
	s_nop 2
	global_load_dword v9, v145, s[6:7] sc1
	v_readlane_b32 s6, v252, 31
	v_readlane_b32 s7, v252, 32
	s_nop 1
	s_nop 2
	global_load_dword v10, v145, s[6:7] sc1
	v_readlane_b32 s6, v252, 33
	v_readlane_b32 s7, v252, 34
	s_nop 1
	s_nop 2
	global_load_dword v11, v145, s[6:7] sc1
	v_readlane_b32 s6, v252, 35
	v_readlane_b32 s7, v252, 36
	s_nop 1
	s_nop 2
	global_load_dword v12, v145, s[6:7] sc1
	v_readlane_b32 s6, v252, 37
	v_readlane_b32 s7, v252, 38
	s_nop 1
	s_nop 2
	global_load_dword v13, v145, s[6:7] sc1
	v_readlane_b32 s6, v252, 39
	v_readlane_b32 s7, v252, 40
	s_nop 1
	s_nop 2
	global_load_dword v14, v145, s[6:7] sc1
	v_readlane_b32 s6, v252, 41
	v_readlane_b32 s7, v252, 42
	s_nop 1
	s_nop 2
	global_load_dword v15, v145, s[6:7] sc1
	s_mov_b64 s[6:7], -1
	s_nop 1
	s_waitcnt vmcnt(0)
	v_add_u32_e32 v16, v1, v0
	v_add_u32_e32 v16, v16, v2
	v_add_u32_e32 v16, v16, v3
	v_add_u32_e32 v16, v16, v4
	v_add_u32_e32 v16, v16, v5
	v_add_u32_e32 v16, v16, v6
	v_add_u32_e32 v16, v16, v7
	v_add_u32_e32 v16, v16, v8
	v_add_u32_e32 v16, v16, v9
	v_add_u32_e32 v16, v16, v10
	v_add_u32_e32 v16, v16, v11
	v_add_u32_e32 v16, v16, v12
	v_add_u32_e32 v16, v16, v13
	v_add_u32_e32 v16, v16, v14
	v_add_u32_e32 v16, v16, v15
	v_cmp_eq_u32_e32 vcc, s60, v16
	s_cbranch_vccnz .LBB0_142
	s_and_b32 s6, s19, 0xff
	s_cmp_eq_u32 s6, 0
	s_mov_b64 s[6:7], -1
	s_mov_b64 s[10:11], -1
	s_sleep 1
	s_cbranch_scc0 .LBB0_147
	v_readlane_b32 s6, v252, 9
	v_readlane_b32 s7, v252, 10
	s_nop 4
	global_load_dword v16, v145, s[6:7] sc1
	s_waitcnt vmcnt(0)
	v_cmp_eq_u32_e32 vcc, 0, v16
	s_cbranch_vccnz .LBB0_149
	s_mov_b64 s[10:11], 0
	s_mov_b64 s[6:7], -1

.LBB0_264:
	s_ashr_i32 s6, s71, 5
	s_add_i32 s8, s6, 16
	v_readlane_b32 s6, v250, 36
	s_ashr_i32 s9, s71, 4
	v_readlane_b32 s7, v250, 37
	s_and_b64 s[6:7], s[6:7], exec
	s_cselect_b32 s6, s9, s8
	s_mul_hi_i32 s7, s6, 0x9000
	s_mul_i32 s6, s6, 0x9000
	v_readlane_b32 s8, v251, 23
	v_lshl_or_b32 v168, s89, 8, v190
	s_add_u32 s6, s8, s6
	v_readlane_b32 s8, v251, 24
	s_addc_u32 s7, s8, s7
	v_ashrrev_i32_e32 v169, 31, v168
	v_lshl_add_u64 v[166:167], v[168:169], 2, s[6:7]
	global_load_dwordx4 v[134:137], v[166:167], off
	global_load_dwordx4 v[192:195], v[166:167], off offset:576
	v_lshl_add_u32 v170, s71, 8, v188
	v_ashrrev_i32_e32 v171, 31, v170
	s_mov_b64 s[6:7], 0x80000
	s_and_b64 vcc, exec, s[42:43]
	s_mov_b32 s89, s69
	s_mov_b32 s71, s70
	s_mov_b64 s[8:9], s[44:45]
	global_load_dwordx4 v[236:239], v[166:167], off offset:64
	global_load_dwordx4 v[240:243], v[166:167], off offset:512
	v_lshlrev_b64 v[166:167], 10, v[170:171]
	v_lshl_add_u64 v[166:167], v[166:167], 0, v[168:169]
	v_lshlrev_b64 v[166:167], 2, v[166:167]
	v_lshl_add_u64 v[196:197], s[38:39], 0, v[166:167]
	v_mov_b64_e32 v[232:233], v[196:197]
	global_load_dwordx4 v[200:203], v[196:197], off
	global_load_dwordx4 v[204:207], v[196:197], off offset:64
	global_load_dwordx4 v[208:211], v[196:197], off offset:512
	global_load_dwordx4 v[212:215], v[196:197], off offset:576
	s_mov_b64 s[98:99], 0x10000
	v_lshl_add_u64 v[234:235], v[232:233], 0, s[98:99]
	global_load_dwordx4 v[216:219], v[234:235], off
	global_load_dwordx4 v[220:223], v[234:235], off offset:64
	global_load_dwordx4 v[224:227], v[234:235], off offset:512
	global_load_dwordx4 v[228:231], v[234:235], off offset:576
	s_waitcnt vmcnt(8)
	v_pk_mul_f32 v[162:163], v[136:137], 0.5 op_sel_hi:[1,0]
	v_pk_mul_f32 v[164:165], v[134:135], 0.5 op_sel_hi:[1,0]
	v_pk_mul_f32 v[160:161], v[238:239], 0.5 op_sel_hi:[1,0]
	v_pk_mul_f32 v[142:143], v[236:237], 0.5 op_sel_hi:[1,0]
	v_pk_mul_f32 v[140:141], v[242:243], 0.5 op_sel_hi:[1,0]
	v_pk_mul_f32 v[138:139], v[240:241], 0.5 op_sel_hi:[1,0]
	v_pk_mul_f32 v[134:135], v[194:195], 0.5 op_sel_hi:[1,0]
	v_pk_mul_f32 v[136:137], v[192:193], 0.5 op_sel_hi:[1,0]
	s_waitcnt vmcnt(7)
	v_pk_fma_f32 v[126:127], v[126:127], v[162:163], v[202:203]
	v_pk_fma_f32 v[124:125], v[124:125], v[164:165], v[200:201]
	v_lshl_add_u64 v[192:193], s[96:97], 0, v[166:167]
	global_store_dwordx4 v[192:193], v[124:127], off
	s_waitcnt vmcnt(7)
	v_pk_fma_f32 v[122:123], v[122:123], v[160:161], v[206:207]
	v_pk_fma_f32 v[120:121], v[120:121], v[142:143], v[204:205]
	global_store_dwordx4 v[192:193], v[120:123], off offset:64
	s_waitcnt vmcnt(7)
	v_pk_fma_f32 v[118:119], v[118:119], v[140:141], v[210:211]
	v_pk_fma_f32 v[116:117], v[116:117], v[138:139], v[208:209]
	global_store_dwordx4 v[192:193], v[116:119], off offset:512
	s_waitcnt vmcnt(7)
	v_pk_fma_f32 v[114:115], v[114:115], v[134:135], v[214:215]
	v_pk_fma_f32 v[112:113], v[112:113], v[136:137], v[212:213]
	global_store_dwordx4 v[192:193], v[112:115], off offset:576
	s_mov_b64 s[98:99], 0x20000
	v_lshl_add_u64 v[234:235], v[232:233], 0, s[98:99]
	global_load_dwordx4 v[200:203], v[234:235], off
	global_load_dwordx4 v[204:207], v[234:235], off offset:64
	global_load_dwordx4 v[208:211], v[234:235], off offset:512
	global_load_dwordx4 v[212:215], v[234:235], off offset:576
	s_nop 1
	v_or_b32_e32 v112, 16, v170
	v_ashrrev_i32_e32 v113, 31, v112
	v_lshlrev_b64 v[112:113], 10, v[112:113]
	v_lshl_add_u64 v[112:113], v[112:113], 0, v[168:169]
	v_lshlrev_b64 v[116:117], 2, v[112:113]
	v_lshl_add_u64 v[118:119], s[38:39], 0, v[116:117]
	s_waitcnt vmcnt(11)
	v_pk_fma_f32 v[110:111], v[110:111], v[162:163], v[218:219]
	v_pk_fma_f32 v[108:109], v[108:109], v[164:165], v[216:217]
	v_lshl_add_u64 v[112:113], s[96:97], 0, v[116:117]
	global_store_dwordx4 v[112:113], v[108:111], off
	s_waitcnt vmcnt(11)
	v_pk_fma_f32 v[106:107], v[106:107], v[160:161], v[222:223]
	v_pk_fma_f32 v[104:105], v[104:105], v[142:143], v[220:221]
	global_store_dwordx4 v[112:113], v[104:107], off offset:64
	s_waitcnt vmcnt(11)
	v_pk_fma_f32 v[102:103], v[102:103], v[140:141], v[226:227]
	v_pk_fma_f32 v[100:101], v[100:101], v[138:139], v[224:225]
	global_store_dwordx4 v[112:113], v[100:103], off offset:512
	s_waitcnt vmcnt(11)
	v_pk_fma_f32 v[98:99], v[98:99], v[134:135], v[230:231]
	v_pk_fma_f32 v[96:97], v[96:97], v[136:137], v[228:229]
	global_store_dwordx4 v[112:113], v[96:99], off offset:576
	s_mov_b64 s[98:99], 0x30000
	v_lshl_add_u64 v[234:235], v[232:233], 0, s[98:99]
	global_load_dwordx4 v[216:219], v[234:235], off
	global_load_dwordx4 v[220:223], v[234:235], off offset:64
	global_load_dwordx4 v[224:227], v[234:235], off offset:512
	global_load_dwordx4 v[228:231], v[234:235], off offset:576
	s_nop 1
	v_or_b32_e32 v96, 32, v170
	v_ashrrev_i32_e32 v97, 31, v96
	v_lshlrev_b64 v[96:97], 10, v[96:97]
	v_lshl_add_u64 v[96:97], v[96:97], 0, v[168:169]
	v_lshlrev_b64 v[100:101], 2, v[96:97]
	v_lshl_add_u64 v[102:103], s[38:39], 0, v[100:101]
	s_waitcnt vmcnt(11)
	v_pk_fma_f32 v[94:95], v[94:95], v[162:163], v[202:203]
	v_pk_fma_f32 v[92:93], v[92:93], v[164:165], v[200:201]
	v_lshl_add_u64 v[96:97], s[96:97], 0, v[100:101]
	global_store_dwordx4 v[96:97], v[92:95], off
	s_waitcnt vmcnt(11)
	v_pk_fma_f32 v[90:91], v[90:91], v[160:161], v[206:207]
	v_pk_fma_f32 v[88:89], v[88:89], v[142:143], v[204:205]
	global_store_dwordx4 v[96:97], v[88:91], off offset:64
	s_waitcnt vmcnt(11)
	v_pk_fma_f32 v[86:87], v[86:87], v[140:141], v[210:211]
	v_pk_fma_f32 v[84:85], v[84:85], v[138:139], v[208:209]
	global_store_dwordx4 v[96:97], v[84:87], off offset:512
	s_waitcnt vmcnt(11)
	v_pk_fma_f32 v[82:83], v[82:83], v[134:135], v[214:215]
	v_pk_fma_f32 v[80:81], v[80:81], v[136:137], v[212:213]
	global_store_dwordx4 v[96:97], v[80:83], off offset:576
	s_mov_b64 s[98:99], 0x80000
	v_lshl_add_u64 v[234:235], v[232:233], 0, s[98:99]
	global_load_dwordx4 v[200:203], v[234:235], off
	global_load_dwordx4 v[204:207], v[234:235], off offset:64
	global_load_dwordx4 v[208:211], v[234:235], off offset:512
	global_load_dwordx4 v[212:215], v[234:235], off offset:576
	s_nop 1
	v_or_b32_e32 v80, 48, v170
	v_ashrrev_i32_e32 v81, 31, v80
	v_lshlrev_b64 v[80:81], 10, v[80:81]
	v_lshl_add_u64 v[80:81], v[80:81], 0, v[168:169]
	v_lshlrev_b64 v[84:85], 2, v[80:81]
	v_lshl_add_u64 v[86:87], s[38:39], 0, v[84:85]
	s_waitcnt vmcnt(11)
	v_pk_fma_f32 v[78:79], v[78:79], v[162:163], v[218:219]
	v_pk_fma_f32 v[76:77], v[76:77], v[164:165], v[216:217]
	v_lshl_add_u64 v[80:81], s[96:97], 0, v[84:85]
	global_store_dwordx4 v[80:81], v[76:79], off
	s_waitcnt vmcnt(11)
	v_pk_fma_f32 v[74:75], v[74:75], v[160:161], v[222:223]
	v_pk_fma_f32 v[72:73], v[72:73], v[142:143], v[220:221]
	global_store_dwordx4 v[80:81], v[72:75], off offset:64
	s_waitcnt vmcnt(11)
	v_pk_fma_f32 v[70:71], v[70:71], v[140:141], v[226:227]
	v_pk_fma_f32 v[68:69], v[68:69], v[138:139], v[224:225]
	global_store_dwordx4 v[80:81], v[68:71], off offset:512
	s_waitcnt vmcnt(11)
	v_pk_fma_f32 v[66:67], v[66:67], v[134:135], v[230:231]
	v_pk_fma_f32 v[64:65], v[64:65], v[136:137], v[228:229]
	v_lshl_add_u64 v[68:69], v[166:167], 0, s[6:7]
	global_store_dwordx4 v[80:81], v[64:67], off offset:576
	s_mov_b64 s[98:99], 0x90000
	v_lshl_add_u64 v[234:235], v[232:233], 0, s[98:99]
	global_load_dwordx4 v[216:219], v[234:235], off
	global_load_dwordx4 v[220:223], v[234:235], off offset:64
	global_load_dwordx4 v[224:227], v[234:235], off offset:512
	global_load_dwordx4 v[228:231], v[234:235], off offset:576
	v_lshl_add_u64 v[70:71], s[38:39], 0, v[68:69]
	s_mov_b64 s[6:7], 0x90000
	s_waitcnt vmcnt(11)
	v_pk_fma_f32 v[62:63], v[62:63], v[162:163], v[202:203]
	v_pk_fma_f32 v[60:61], v[60:61], v[164:165], v[200:201]
	v_lshl_add_u64 v[64:65], s[96:97], 0, v[68:69]
	global_store_dwordx4 v[64:65], v[60:63], off
	s_waitcnt vmcnt(11)
	v_pk_fma_f32 v[58:59], v[58:59], v[160:161], v[206:207]
	v_pk_fma_f32 v[56:57], v[56:57], v[142:143], v[204:205]
	global_store_dwordx4 v[64:65], v[56:59], off offset:64
	s_waitcnt vmcnt(11)
	v_pk_fma_f32 v[54:55], v[54:55], v[140:141], v[210:211]
	v_pk_fma_f32 v[52:53], v[52:53], v[138:139], v[208:209]
	global_store_dwordx4 v[64:65], v[52:55], off offset:512
	s_waitcnt vmcnt(11)
	v_pk_fma_f32 v[50:51], v[50:51], v[134:135], v[214:215]
	v_pk_fma_f32 v[48:49], v[48:49], v[136:137], v[212:213]
	v_lshl_add_u64 v[52:53], v[166:167], 0, s[6:7]
	global_store_dwordx4 v[64:65], v[48:51], off offset:576
	s_mov_b64 s[98:99], 0xa0000
	v_lshl_add_u64 v[234:235], v[232:233], 0, s[98:99]
	global_load_dwordx4 v[200:203], v[234:235], off
	global_load_dwordx4 v[204:207], v[234:235], off offset:64
	global_load_dwordx4 v[208:211], v[234:235], off offset:512
	global_load_dwordx4 v[212:215], v[234:235], off offset:576
	v_lshl_add_u64 v[54:55], s[38:39], 0, v[52:53]
	s_mov_b64 s[6:7], 0xa0000
	s_waitcnt vmcnt(11)
	v_pk_fma_f32 v[46:47], v[46:47], v[162:163], v[218:219]
	v_pk_fma_f32 v[44:45], v[44:45], v[164:165], v[216:217]
	v_lshl_add_u64 v[48:49], s[96:97], 0, v[52:53]
	global_store_dwordx4 v[48:49], v[44:47], off
	s_waitcnt vmcnt(11)
	v_pk_fma_f32 v[42:43], v[42:43], v[160:161], v[222:223]
	v_pk_fma_f32 v[40:41], v[40:41], v[142:143], v[220:221]
	global_store_dwordx4 v[48:49], v[40:43], off offset:64
	s_waitcnt vmcnt(11)
	v_pk_fma_f32 v[38:39], v[38:39], v[140:141], v[226:227]
	v_pk_fma_f32 v[36:37], v[36:37], v[138:139], v[224:225]
	global_store_dwordx4 v[48:49], v[36:39], off offset:512
	s_waitcnt vmcnt(11)
	v_pk_fma_f32 v[34:35], v[34:35], v[134:135], v[230:231]
	v_pk_fma_f32 v[32:33], v[32:33], v[136:137], v[228:229]
	v_lshl_add_u64 v[36:37], v[166:167], 0, s[6:7]
	global_store_dwordx4 v[48:49], v[32:35], off offset:576
	s_mov_b64 s[98:99], 0xb0000
	v_lshl_add_u64 v[234:235], v[232:233], 0, s[98:99]
	global_load_dwordx4 v[216:219], v[234:235], off
	global_load_dwordx4 v[220:223], v[234:235], off offset:64
	global_load_dwordx4 v[224:227], v[234:235], off offset:512
	global_load_dwordx4 v[228:231], v[234:235], off offset:576
	v_lshl_add_u64 v[38:39], s[38:39], 0, v[36:37]
	s_mov_b64 s[6:7], 0xb0000
	s_waitcnt vmcnt(11)
	v_pk_fma_f32 v[30:31], v[30:31], v[162:163], v[202:203]
	v_pk_fma_f32 v[28:29], v[28:29], v[164:165], v[200:201]
	v_lshl_add_u64 v[32:33], s[96:97], 0, v[36:37]
	global_store_dwordx4 v[32:33], v[28:31], off
	s_waitcnt vmcnt(11)
	v_pk_fma_f32 v[26:27], v[26:27], v[160:161], v[206:207]
	v_pk_fma_f32 v[24:25], v[24:25], v[142:143], v[204:205]
	global_store_dwordx4 v[32:33], v[24:27], off offset:64
	s_waitcnt vmcnt(11)
	v_pk_fma_f32 v[22:23], v[22:23], v[140:141], v[210:211]
	v_pk_fma_f32 v[20:21], v[20:21], v[138:139], v[208:209]
	global_store_dwordx4 v[32:33], v[20:23], off offset:512
	s_waitcnt vmcnt(11)
	v_pk_fma_f32 v[18:19], v[18:19], v[134:135], v[214:215]
	v_pk_fma_f32 v[16:17], v[16:17], v[136:137], v[212:213]
	v_lshl_add_u64 v[20:21], v[166:167], 0, s[6:7]
	global_store_dwordx4 v[32:33], v[16:19], off offset:576
	v_lshl_add_u64 v[22:23], s[38:39], 0, v[20:21]
	s_mov_b64 s[6:7], s[46:47]
	s_waitcnt vmcnt(7)
	v_pk_fma_f32 v[14:15], v[14:15], v[162:163], v[218:219]
	v_pk_fma_f32 v[12:13], v[12:13], v[164:165], v[216:217]
	v_lshl_add_u64 v[16:17], s[96:97], 0, v[20:21]
	global_store_dwordx4 v[16:17], v[12:15], off
	s_waitcnt vmcnt(7)
	v_pk_fma_f32 v[10:11], v[10:11], v[160:161], v[222:223]
	v_pk_fma_f32 v[8:9], v[8:9], v[142:143], v[220:221]
	global_store_dwordx4 v[16:17], v[8:11], off offset:64
	s_waitcnt vmcnt(7)
	v_pk_fma_f32 v[6:7], v[6:7], v[140:141], v[226:227]
	v_pk_fma_f32 v[4:5], v[4:5], v[138:139], v[224:225]
	global_store_dwordx4 v[16:17], v[4:7], off offset:512
	s_waitcnt vmcnt(7)
	v_pk_fma_f32 v[2:3], v[2:3], v[134:135], v[230:231]
	v_pk_fma_f32 v[0:1], v[0:1], v[136:137], v[228:229]
	global_store_dwordx4 v[16:17], v[0:3], off offset:576
	s_cbranch_vccnz .LBB0_278

.LBB0_922:
	s_ashr_i32 s6, s69, 5
	s_add_i32 s8, s6, 16
	v_readlane_b32 s6, v250, 36
	s_ashr_i32 s9, s69, 4
	v_readlane_b32 s7, v250, 37
	s_and_b64 s[6:7], s[6:7], exec
	s_cselect_b32 s6, s9, s8
	v_lshl_add_u32 v170, s69, 8, v188
	v_lshl_or_b32 v80, s70, 8, v190
	s_mul_hi_i32 s7, s6, 0x9000
	s_mul_i32 s6, s6, 0x9000
	v_readlane_b32 s8, v251, 46
	v_ashrrev_i32_e32 v171, 31, v170
	s_add_u32 s6, s8, s6
	v_readlane_b32 s8, v251, 47
	v_ashrrev_i32_e32 v81, 31, v80
	v_lshlrev_b64 v[166:167], 12, v[170:171]
	s_addc_u32 s7, s8, s7
	v_lshlrev_b64 v[168:169], 2, v[80:81]
	v_lshl_add_u64 v[166:167], s[96:97], 0, v[166:167]
	v_lshl_add_u64 v[80:81], s[6:7], 0, v[168:169]
	v_lshl_add_u64 v[166:167], v[166:167], 0, v[168:169]
	global_load_dwordx4 v[140:143], v[80:81], off
	global_load_dwordx4 v[136:139], v[80:81], off offset:64
	global_load_dwordx4 v[132:135], v[80:81], off offset:512
	s_nop 0
	global_load_dwordx4 v[80:83], v[80:81], off offset:576
	s_mov_b64 s[6:7], 0x80000
	v_mov_b64_e32 v[232:233], v[166:167]
	global_load_dwordx4 v[200:203], v[166:167], off
	global_load_dwordx4 v[204:207], v[166:167], off offset:64
	global_load_dwordx4 v[208:211], v[166:167], off offset:512
	global_load_dwordx4 v[212:215], v[166:167], off offset:576
	s_mov_b64 s[98:99], 0x10000
	v_lshl_add_u64 v[234:235], v[232:233], 0, s[98:99]
	global_load_dwordx4 v[216:219], v[234:235], off
	global_load_dwordx4 v[220:223], v[234:235], off offset:64
	global_load_dwordx4 v[224:227], v[234:235], off offset:512
	global_load_dwordx4 v[228:231], v[234:235], off offset:576
	s_mov_b32 s70, s61
	s_mov_b32 s69, s68
	s_mov_b64 s[8:9], s[44:45]
	s_waitcnt vmcnt(7)
	v_pk_fma_f32 v[130:131], v[130:131], v[142:143], v[202:203]
	v_pk_fma_f32 v[128:129], v[128:129], v[140:141], v[200:201]
	global_store_dwordx4 v[166:167], v[128:131], off
	s_waitcnt vmcnt(7)
	v_pk_fma_f32 v[126:127], v[126:127], v[138:139], v[206:207]
	v_pk_fma_f32 v[124:125], v[124:125], v[136:137], v[204:205]
	global_store_dwordx4 v[166:167], v[124:127], off offset:64
	s_waitcnt vmcnt(7)
	v_pk_fma_f32 v[122:123], v[122:123], v[134:135], v[210:211]
	v_pk_fma_f32 v[120:121], v[120:121], v[132:133], v[208:209]
	global_store_dwordx4 v[166:167], v[120:123], off offset:512
	s_waitcnt vmcnt(7)
	v_pk_fma_f32 v[118:119], v[118:119], v[82:83], v[214:215]
	v_pk_fma_f32 v[116:117], v[116:117], v[80:81], v[212:213]
	global_store_dwordx4 v[166:167], v[116:119], off offset:576
	s_mov_b64 s[98:99], 0x20000
	v_lshl_add_u64 v[234:235], v[232:233], 0, s[98:99]
	global_load_dwordx4 v[200:203], v[234:235], off
	global_load_dwordx4 v[204:207], v[234:235], off offset:64
	global_load_dwordx4 v[208:211], v[234:235], off offset:512
	global_load_dwordx4 v[212:215], v[234:235], off offset:576
	s_nop 1
	v_or_b32_e32 v116, 16, v170
	v_ashrrev_i32_e32 v117, 31, v116
	v_lshlrev_b64 v[116:117], 12, v[116:117]
	v_lshl_add_u64 v[116:117], s[96:97], 0, v[116:117]
	v_lshl_add_u64 v[120:121], v[116:117], 0, v[168:169]
	s_waitcnt vmcnt(11)
	v_pk_fma_f32 v[114:115], v[114:115], v[142:143], v[218:219]
	v_pk_fma_f32 v[112:113], v[112:113], v[140:141], v[216:217]
	global_store_dwordx4 v[120:121], v[112:115], off
	s_waitcnt vmcnt(11)
	v_pk_fma_f32 v[110:111], v[110:111], v[138:139], v[222:223]
	v_pk_fma_f32 v[108:109], v[108:109], v[136:137], v[220:221]
	global_store_dwordx4 v[120:121], v[108:111], off offset:64
	s_waitcnt vmcnt(11)
	v_pk_fma_f32 v[106:107], v[106:107], v[134:135], v[226:227]
	v_pk_fma_f32 v[104:105], v[104:105], v[132:133], v[224:225]
	global_store_dwordx4 v[120:121], v[104:107], off offset:512
	s_waitcnt vmcnt(11)
	v_pk_fma_f32 v[102:103], v[102:103], v[82:83], v[230:231]
	v_pk_fma_f32 v[100:101], v[100:101], v[80:81], v[228:229]
	global_store_dwordx4 v[120:121], v[100:103], off offset:576
	s_mov_b64 s[98:99], 0x30000
	v_lshl_add_u64 v[234:235], v[232:233], 0, s[98:99]
	global_load_dwordx4 v[216:219], v[234:235], off
	global_load_dwordx4 v[220:223], v[234:235], off offset:64
	global_load_dwordx4 v[224:227], v[234:235], off offset:512
	global_load_dwordx4 v[228:231], v[234:235], off offset:576
	s_nop 1
	v_or_b32_e32 v100, 32, v170
	v_ashrrev_i32_e32 v101, 31, v100
	v_lshlrev_b64 v[100:101], 12, v[100:101]
	v_lshl_add_u64 v[100:101], s[96:97], 0, v[100:101]
	v_lshl_add_u64 v[104:105], v[100:101], 0, v[168:169]
	s_waitcnt vmcnt(11)
	v_pk_fma_f32 v[98:99], v[98:99], v[142:143], v[202:203]
	v_pk_fma_f32 v[96:97], v[96:97], v[140:141], v[200:201]
	global_store_dwordx4 v[104:105], v[96:99], off
	s_waitcnt vmcnt(11)
	v_pk_fma_f32 v[94:95], v[94:95], v[138:139], v[206:207]
	v_pk_fma_f32 v[92:93], v[92:93], v[136:137], v[204:205]
	global_store_dwordx4 v[104:105], v[92:95], off offset:64
	s_waitcnt vmcnt(11)
	v_pk_fma_f32 v[90:91], v[90:91], v[134:135], v[210:211]
	v_pk_fma_f32 v[88:89], v[88:89], v[132:133], v[208:209]
	global_store_dwordx4 v[104:105], v[88:91], off offset:512
	s_waitcnt vmcnt(11)
	v_pk_fma_f32 v[86:87], v[86:87], v[82:83], v[214:215]
	v_pk_fma_f32 v[84:85], v[84:85], v[80:81], v[212:213]
	global_store_dwordx4 v[104:105], v[84:87], off offset:576
	s_mov_b64 s[98:99], 0x80000
	v_lshl_add_u64 v[234:235], v[232:233], 0, s[98:99]
	global_load_dwordx4 v[200:203], v[234:235], off
	global_load_dwordx4 v[204:207], v[234:235], off offset:64
	global_load_dwordx4 v[208:211], v[234:235], off offset:512
	global_load_dwordx4 v[212:215], v[234:235], off offset:576
	s_nop 1
	v_or_b32_e32 v84, 48, v170
	v_ashrrev_i32_e32 v85, 31, v84
	v_lshlrev_b64 v[84:85], 12, v[84:85]
	v_lshl_add_u64 v[84:85], s[96:97], 0, v[84:85]
	v_lshl_add_u64 v[88:89], v[84:85], 0, v[168:169]
	s_waitcnt vmcnt(11)
	v_pk_fma_f32 v[78:79], v[78:79], v[142:143], v[218:219]
	v_pk_fma_f32 v[76:77], v[76:77], v[140:141], v[216:217]
	global_store_dwordx4 v[88:89], v[76:79], off
	s_waitcnt vmcnt(11)
	v_pk_fma_f32 v[74:75], v[74:75], v[138:139], v[222:223]
	v_pk_fma_f32 v[72:73], v[72:73], v[136:137], v[220:221]
	global_store_dwordx4 v[88:89], v[72:75], off offset:64
	s_waitcnt vmcnt(11)
	v_pk_fma_f32 v[70:71], v[70:71], v[134:135], v[226:227]
	v_pk_fma_f32 v[68:69], v[68:69], v[132:133], v[224:225]
	global_store_dwordx4 v[88:89], v[68:71], off offset:512
	s_waitcnt vmcnt(11)
	v_pk_fma_f32 v[64:65], v[64:65], v[80:81], v[228:229]
	v_lshl_add_u64 v[68:69], v[166:167], 0, s[6:7]
	s_mov_b32 s6, 0x80000
	v_pk_fma_f32 v[66:67], v[66:67], v[82:83], v[230:231]
	v_add_co_u32_e32 v70, vcc, s6, v166
	global_store_dwordx4 v[88:89], v[64:67], off offset:576
	s_mov_b64 s[98:99], 0x90000
	v_lshl_add_u64 v[234:235], v[232:233], 0, s[98:99]
	global_load_dwordx4 v[216:219], v[234:235], off
	global_load_dwordx4 v[220:223], v[234:235], off offset:64
	global_load_dwordx4 v[224:227], v[234:235], off offset:512
	global_load_dwordx4 v[228:231], v[234:235], off offset:576
	s_nop 0
	v_addc_co_u32_e32 v71, vcc, 0, v167, vcc
	s_mov_b64 s[6:7], 0x90000
	s_waitcnt vmcnt(11)
	v_pk_fma_f32 v[62:63], v[62:63], v[142:143], v[202:203]
	v_pk_fma_f32 v[60:61], v[60:61], v[140:141], v[200:201]
	global_store_dwordx4 v[70:71], v[60:63], off
	s_waitcnt vmcnt(11)
	v_pk_fma_f32 v[58:59], v[58:59], v[138:139], v[206:207]
	v_pk_fma_f32 v[56:57], v[56:57], v[136:137], v[204:205]
	global_store_dwordx4 v[68:69], v[56:59], off offset:64
	s_waitcnt vmcnt(11)
	v_pk_fma_f32 v[54:55], v[54:55], v[134:135], v[210:211]
	v_pk_fma_f32 v[52:53], v[52:53], v[132:133], v[208:209]
	global_store_dwordx4 v[68:69], v[52:55], off offset:512
	s_waitcnt vmcnt(11)
	v_pk_fma_f32 v[48:49], v[48:49], v[80:81], v[212:213]
	v_lshl_add_u64 v[52:53], v[166:167], 0, s[6:7]
	s_mov_b32 s6, 0x90000
	v_pk_fma_f32 v[50:51], v[50:51], v[82:83], v[214:215]
	v_add_co_u32_e32 v54, vcc, s6, v166
	global_store_dwordx4 v[68:69], v[48:51], off offset:576
	s_mov_b64 s[98:99], 0xa0000
	v_lshl_add_u64 v[234:235], v[232:233], 0, s[98:99]
	global_load_dwordx4 v[200:203], v[234:235], off
	global_load_dwordx4 v[204:207], v[234:235], off offset:64
	global_load_dwordx4 v[208:211], v[234:235], off offset:512
	global_load_dwordx4 v[212:215], v[234:235], off offset:576
	s_nop 0
	v_addc_co_u32_e32 v55, vcc, 0, v167, vcc
	s_mov_b64 s[6:7], 0xa0000
	s_waitcnt vmcnt(11)
	v_pk_fma_f32 v[46:47], v[46:47], v[142:143], v[218:219]
	v_pk_fma_f32 v[44:45], v[44:45], v[140:141], v[216:217]
	global_store_dwordx4 v[54:55], v[44:47], off
	s_waitcnt vmcnt(11)
	v_pk_fma_f32 v[42:43], v[42:43], v[138:139], v[222:223]
	v_pk_fma_f32 v[40:41], v[40:41], v[136:137], v[220:221]
	global_store_dwordx4 v[52:53], v[40:43], off offset:64
	s_waitcnt vmcnt(11)
	v_pk_fma_f32 v[38:39], v[38:39], v[134:135], v[226:227]
	v_pk_fma_f32 v[36:37], v[36:37], v[132:133], v[224:225]
	global_store_dwordx4 v[52:53], v[36:39], off offset:512
	s_waitcnt vmcnt(11)
	v_pk_fma_f32 v[34:35], v[34:35], v[82:83], v[230:231]
	v_pk_fma_f32 v[32:33], v[32:33], v[80:81], v[228:229]
	global_store_dwordx4 v[52:53], v[32:35], off offset:576
	s_mov_b64 s[98:99], 0xb0000
	v_lshl_add_u64 v[234:235], v[232:233], 0, s[98:99]
	global_load_dwordx4 v[216:219], v[234:235], off
	global_load_dwordx4 v[220:223], v[234:235], off offset:64
	global_load_dwordx4 v[224:227], v[234:235], off offset:512
	global_load_dwordx4 v[228:231], v[234:235], off offset:576
	s_nop 1
	v_lshl_add_u64 v[32:33], v[166:167], 0, s[6:7]
	s_mov_b32 s6, 0xa0000
	v_add_co_u32_e32 v38, vcc, s6, v166
	s_mov_b64 s[6:7], 0xb0000
	s_nop 0
	v_addc_co_u32_e32 v39, vcc, 0, v167, vcc
	s_waitcnt vmcnt(11)
	v_pk_fma_f32 v[30:31], v[30:31], v[142:143], v[202:203]
	v_pk_fma_f32 v[28:29], v[28:29], v[140:141], v[200:201]
	global_store_dwordx4 v[38:39], v[28:31], off
	s_waitcnt vmcnt(11)
	v_pk_fma_f32 v[26:27], v[26:27], v[138:139], v[206:207]
	v_pk_fma_f32 v[24:25], v[24:25], v[136:137], v[204:205]
	global_store_dwordx4 v[32:33], v[24:27], off offset:64
	s_waitcnt vmcnt(11)
	v_pk_fma_f32 v[22:23], v[22:23], v[134:135], v[210:211]
	v_pk_fma_f32 v[20:21], v[20:21], v[132:133], v[208:209]
	global_store_dwordx4 v[32:33], v[20:23], off offset:512
	s_waitcnt vmcnt(11)
	v_pk_fma_f32 v[18:19], v[18:19], v[82:83], v[214:215]
	v_pk_fma_f32 v[16:17], v[16:17], v[80:81], v[212:213]
	global_store_dwordx4 v[32:33], v[16:19], off offset:576
	s_nop 1
	v_lshl_add_u64 v[16:17], v[166:167], 0, s[6:7]
	s_mov_b32 s6, 0xb0000
	v_add_co_u32_e32 v22, vcc, s6, v166
	s_mov_b64 s[6:7], s[46:47]
	s_nop 0
	v_addc_co_u32_e32 v23, vcc, 0, v167, vcc
	s_and_b64 vcc, exec, s[42:43]
	s_waitcnt vmcnt(7)
	v_pk_fma_f32 v[14:15], v[14:15], v[142:143], v[218:219]
	v_pk_fma_f32 v[12:13], v[12:13], v[140:141], v[216:217]
	global_store_dwordx4 v[22:23], v[12:15], off
	s_waitcnt vmcnt(7)
	v_pk_fma_f32 v[10:11], v[10:11], v[138:139], v[222:223]
	v_pk_fma_f32 v[8:9], v[8:9], v[136:137], v[220:221]
	global_store_dwordx4 v[16:17], v[8:11], off offset:64
	s_waitcnt vmcnt(7)
	v_pk_fma_f32 v[6:7], v[6:7], v[134:135], v[226:227]
	v_pk_fma_f32 v[4:5], v[4:5], v[132:133], v[224:225]
	global_store_dwordx4 v[16:17], v[4:7], off offset:512
	s_waitcnt vmcnt(7)
	v_pk_fma_f32 v[2:3], v[2:3], v[82:83], v[230:231]
	v_pk_fma_f32 v[0:1], v[0:1], v[80:81], v[228:229]
	global_store_dwordx4 v[16:17], v[0:3], off offset:576
	s_cbranch_vccnz .LBB0_936

.LBB0_1119:
	s_ashr_i32 s6, s69, 5
	s_add_i32 s8, s6, 16
	v_readlane_b32 s6, v250, 36
	s_ashr_i32 s9, s69, 4
	v_readlane_b32 s7, v250, 37
	s_and_b64 s[6:7], s[6:7], exec
	s_cselect_b32 s6, s9, s8
	v_lshl_or_b32 v134, s70, 8, v190
	s_mul_hi_i32 s7, s6, 0x9000
	s_mul_i32 s6, s6, 0x9000
	v_readlane_b32 s8, v251, 52
	s_add_u32 s6, s8, s6
	v_readlane_b32 s8, v251, 53
	v_ashrrev_i32_e32 v135, 31, v134
	s_addc_u32 s7, s8, s7
	v_lshlrev_b64 v[168:169], 2, v[134:135]
	v_lshl_add_u64 v[166:167], s[6:7], 0, v[168:169]
	global_load_dwordx4 v[134:137], v[166:167], off
	v_lshl_add_u32 v170, s69, 8, v188
	v_ashrrev_i32_e32 v171, 31, v170
	s_mov_b64 s[6:7], 0x80000
	s_mov_b32 s70, s61
	s_mov_b32 s69, s68
	s_mov_b64 s[8:9], s[40:41]
	global_load_dwordx4 v[236:239], v[166:167], off offset:64
	global_load_dwordx4 v[240:243], v[166:167], off offset:512
	global_load_dwordx4 v[244:247], v[166:167], off offset:576
	v_lshlrev_b64 v[166:167], 12, v[170:171]
	v_lshl_add_u64 v[166:167], s[96:97], 0, v[166:167]
	v_lshl_add_u64 v[166:167], v[166:167], 0, v[168:169]
	v_mov_b64_e32 v[232:233], v[166:167]
	global_load_dwordx4 v[200:203], v[166:167], off
	global_load_dwordx4 v[204:207], v[166:167], off offset:64
	global_load_dwordx4 v[208:211], v[166:167], off offset:512
	global_load_dwordx4 v[212:215], v[166:167], off offset:576
	s_mov_b64 s[98:99], 0x10000
	v_lshl_add_u64 v[234:235], v[232:233], 0, s[98:99]
	global_load_dwordx4 v[216:219], v[234:235], off
	global_load_dwordx4 v[220:223], v[234:235], off offset:64
	global_load_dwordx4 v[224:227], v[234:235], off offset:512
	global_load_dwordx4 v[228:231], v[234:235], off offset:576
	s_waitcnt vmcnt(8)
	v_pk_mul_f32 v[162:163], v[136:137], 0.5 op_sel_hi:[1,0]
	v_pk_mul_f32 v[164:165], v[134:135], 0.5 op_sel_hi:[1,0]
	v_pk_mul_f32 v[142:143], v[238:239], 0.5 op_sel_hi:[1,0]
	v_pk_mul_f32 v[160:161], v[236:237], 0.5 op_sel_hi:[1,0]
	v_pk_mul_f32 v[138:139], v[242:243], 0.5 op_sel_hi:[1,0]
	v_pk_mul_f32 v[140:141], v[240:241], 0.5 op_sel_hi:[1,0]
	v_pk_mul_f32 v[136:137], v[246:247], 0.5 op_sel_hi:[1,0]
	v_pk_mul_f32 v[134:135], v[244:245], 0.5 op_sel_hi:[1,0]
	s_waitcnt vmcnt(7)
	v_pk_fma_f32 v[126:127], v[126:127], v[162:163], v[202:203]
	v_pk_fma_f32 v[124:125], v[124:125], v[164:165], v[200:201]
	global_store_dwordx4 v[166:167], v[124:127], off
	s_waitcnt vmcnt(7)
	v_pk_fma_f32 v[122:123], v[122:123], v[142:143], v[206:207]
	v_pk_fma_f32 v[120:121], v[120:121], v[160:161], v[204:205]
	global_store_dwordx4 v[166:167], v[120:123], off offset:64
	s_waitcnt vmcnt(7)
	v_pk_fma_f32 v[118:119], v[118:119], v[138:139], v[210:211]
	v_pk_fma_f32 v[116:117], v[116:117], v[140:141], v[208:209]
	global_store_dwordx4 v[166:167], v[116:119], off offset:512
	s_waitcnt vmcnt(7)
	v_pk_fma_f32 v[114:115], v[114:115], v[136:137], v[214:215]
	v_pk_fma_f32 v[112:113], v[112:113], v[134:135], v[212:213]
	global_store_dwordx4 v[166:167], v[112:115], off offset:576
	s_mov_b64 s[98:99], 0x20000
	v_lshl_add_u64 v[234:235], v[232:233], 0, s[98:99]
	global_load_dwordx4 v[200:203], v[234:235], off
	global_load_dwordx4 v[204:207], v[234:235], off offset:64
	global_load_dwordx4 v[208:211], v[234:235], off offset:512
	global_load_dwordx4 v[212:215], v[234:235], off offset:576
	s_nop 1
	v_or_b32_e32 v112, 16, v170
	v_ashrrev_i32_e32 v113, 31, v112
	v_lshlrev_b64 v[112:113], 12, v[112:113]
	v_lshl_add_u64 v[112:113], s[96:97], 0, v[112:113]
	v_lshl_add_u64 v[116:117], v[112:113], 0, v[168:169]
	s_waitcnt vmcnt(11)
	v_pk_fma_f32 v[110:111], v[110:111], v[162:163], v[218:219]
	v_pk_fma_f32 v[108:109], v[108:109], v[164:165], v[216:217]
	global_store_dwordx4 v[116:117], v[108:111], off
	s_waitcnt vmcnt(11)
	v_pk_fma_f32 v[106:107], v[106:107], v[142:143], v[222:223]
	v_pk_fma_f32 v[104:105], v[104:105], v[160:161], v[220:221]
	global_store_dwordx4 v[116:117], v[104:107], off offset:64
	s_waitcnt vmcnt(11)
	v_pk_fma_f32 v[102:103], v[102:103], v[138:139], v[226:227]
	v_pk_fma_f32 v[100:101], v[100:101], v[140:141], v[224:225]
	global_store_dwordx4 v[116:117], v[100:103], off offset:512
	s_waitcnt vmcnt(11)
	v_pk_fma_f32 v[98:99], v[98:99], v[136:137], v[230:231]
	v_pk_fma_f32 v[96:97], v[96:97], v[134:135], v[228:229]
	global_store_dwordx4 v[116:117], v[96:99], off offset:576
	s_mov_b64 s[98:99], 0x30000
	v_lshl_add_u64 v[234:235], v[232:233], 0, s[98:99]
	global_load_dwordx4 v[216:219], v[234:235], off
	global_load_dwordx4 v[220:223], v[234:235], off offset:64
	global_load_dwordx4 v[224:227], v[234:235], off offset:512
	global_load_dwordx4 v[228:231], v[234:235], off offset:576
	s_nop 1
	v_or_b32_e32 v96, 32, v170
	v_ashrrev_i32_e32 v97, 31, v96
	v_lshlrev_b64 v[96:97], 12, v[96:97]
	v_lshl_add_u64 v[96:97], s[96:97], 0, v[96:97]
	v_lshl_add_u64 v[100:101], v[96:97], 0, v[168:169]
	s_waitcnt vmcnt(11)
	v_pk_fma_f32 v[94:95], v[94:95], v[162:163], v[202:203]
	v_pk_fma_f32 v[92:93], v[92:93], v[164:165], v[200:201]
	global_store_dwordx4 v[100:101], v[92:95], off
	s_waitcnt vmcnt(11)
	v_pk_fma_f32 v[90:91], v[90:91], v[142:143], v[206:207]
	v_pk_fma_f32 v[88:89], v[88:89], v[160:161], v[204:205]
	global_store_dwordx4 v[100:101], v[88:91], off offset:64
	s_waitcnt vmcnt(11)
	v_pk_fma_f32 v[86:87], v[86:87], v[138:139], v[210:211]
	v_pk_fma_f32 v[84:85], v[84:85], v[140:141], v[208:209]
	global_store_dwordx4 v[100:101], v[84:87], off offset:512
	s_waitcnt vmcnt(11)
	v_pk_fma_f32 v[82:83], v[82:83], v[136:137], v[214:215]
	v_pk_fma_f32 v[80:81], v[80:81], v[134:135], v[212:213]
	global_store_dwordx4 v[100:101], v[80:83], off offset:576
	s_mov_b64 s[98:99], 0x80000
	v_lshl_add_u64 v[234:235], v[232:233], 0, s[98:99]
	global_load_dwordx4 v[200:203], v[234:235], off
	global_load_dwordx4 v[204:207], v[234:235], off offset:64
	global_load_dwordx4 v[208:211], v[234:235], off offset:512
	global_load_dwordx4 v[212:215], v[234:235], off offset:576
	s_nop 1
	v_or_b32_e32 v80, 48, v170
	v_ashrrev_i32_e32 v81, 31, v80
	v_lshlrev_b64 v[80:81], 12, v[80:81]
	v_lshl_add_u64 v[80:81], s[96:97], 0, v[80:81]
	v_lshl_add_u64 v[84:85], v[80:81], 0, v[168:169]
	s_waitcnt vmcnt(11)
	v_pk_fma_f32 v[78:79], v[78:79], v[162:163], v[218:219]
	v_pk_fma_f32 v[76:77], v[76:77], v[164:165], v[216:217]
	global_store_dwordx4 v[84:85], v[76:79], off
	s_waitcnt vmcnt(11)
	v_pk_fma_f32 v[74:75], v[74:75], v[142:143], v[222:223]
	v_pk_fma_f32 v[72:73], v[72:73], v[160:161], v[220:221]
	global_store_dwordx4 v[84:85], v[72:75], off offset:64
	s_waitcnt vmcnt(11)
	v_pk_fma_f32 v[70:71], v[70:71], v[138:139], v[226:227]
	v_pk_fma_f32 v[68:69], v[68:69], v[140:141], v[224:225]
	global_store_dwordx4 v[84:85], v[68:71], off offset:512
	s_waitcnt vmcnt(11)
	v_pk_fma_f32 v[64:65], v[64:65], v[134:135], v[228:229]
	v_lshl_add_u64 v[68:69], v[166:167], 0, s[6:7]
	s_mov_b32 s6, 0x80000
	v_pk_fma_f32 v[66:67], v[66:67], v[136:137], v[230:231]
	v_add_co_u32_e32 v70, vcc, s6, v166
	global_store_dwordx4 v[84:85], v[64:67], off offset:576
	s_mov_b64 s[98:99], 0x90000
	v_lshl_add_u64 v[234:235], v[232:233], 0, s[98:99]
	global_load_dwordx4 v[216:219], v[234:235], off
	global_load_dwordx4 v[220:223], v[234:235], off offset:64
	global_load_dwordx4 v[224:227], v[234:235], off offset:512
	global_load_dwordx4 v[228:231], v[234:235], off offset:576
	s_nop 0
	v_addc_co_u32_e32 v71, vcc, 0, v167, vcc
	s_mov_b64 s[6:7], 0x90000
	s_waitcnt vmcnt(11)
	v_pk_fma_f32 v[62:63], v[62:63], v[162:163], v[202:203]
	v_pk_fma_f32 v[60:61], v[60:61], v[164:165], v[200:201]
	global_store_dwordx4 v[70:71], v[60:63], off
	s_waitcnt vmcnt(11)
	v_pk_fma_f32 v[58:59], v[58:59], v[142:143], v[206:207]
	v_pk_fma_f32 v[56:57], v[56:57], v[160:161], v[204:205]
	global_store_dwordx4 v[68:69], v[56:59], off offset:64
	s_waitcnt vmcnt(11)
	v_pk_fma_f32 v[54:55], v[54:55], v[138:139], v[210:211]
	v_pk_fma_f32 v[52:53], v[52:53], v[140:141], v[208:209]
	global_store_dwordx4 v[68:69], v[52:55], off offset:512
	s_waitcnt vmcnt(11)
	v_pk_fma_f32 v[48:49], v[48:49], v[134:135], v[212:213]
	v_lshl_add_u64 v[52:53], v[166:167], 0, s[6:7]
	s_mov_b32 s6, 0x90000
	v_pk_fma_f32 v[50:51], v[50:51], v[136:137], v[214:215]
	v_add_co_u32_e32 v54, vcc, s6, v166
	global_store_dwordx4 v[68:69], v[48:51], off offset:576
	s_mov_b64 s[98:99], 0xa0000
	v_lshl_add_u64 v[234:235], v[232:233], 0, s[98:99]
	global_load_dwordx4 v[200:203], v[234:235], off
	global_load_dwordx4 v[204:207], v[234:235], off offset:64
	global_load_dwordx4 v[208:211], v[234:235], off offset:512
	global_load_dwordx4 v[212:215], v[234:235], off offset:576
	s_nop 0
	v_addc_co_u32_e32 v55, vcc, 0, v167, vcc
	s_mov_b64 s[6:7], 0xa0000
	s_waitcnt vmcnt(11)
	v_pk_fma_f32 v[46:47], v[46:47], v[162:163], v[218:219]
	v_pk_fma_f32 v[44:45], v[44:45], v[164:165], v[216:217]
	global_store_dwordx4 v[54:55], v[44:47], off
	s_waitcnt vmcnt(11)
	v_pk_fma_f32 v[42:43], v[42:43], v[142:143], v[222:223]
	v_pk_fma_f32 v[40:41], v[40:41], v[160:161], v[220:221]
	global_store_dwordx4 v[52:53], v[40:43], off offset:64
	s_waitcnt vmcnt(11)
	v_pk_fma_f32 v[38:39], v[38:39], v[138:139], v[226:227]
	v_pk_fma_f32 v[36:37], v[36:37], v[140:141], v[224:225]
	global_store_dwordx4 v[52:53], v[36:39], off offset:512
	s_waitcnt vmcnt(11)
	v_pk_fma_f32 v[32:33], v[32:33], v[134:135], v[228:229]
	v_lshl_add_u64 v[36:37], v[166:167], 0, s[6:7]
	s_mov_b32 s6, 0xa0000
	v_pk_fma_f32 v[34:35], v[34:35], v[136:137], v[230:231]
	v_add_co_u32_e32 v38, vcc, s6, v166
	global_store_dwordx4 v[52:53], v[32:35], off offset:576
	s_mov_b64 s[98:99], 0xb0000
	v_lshl_add_u64 v[234:235], v[232:233], 0, s[98:99]
	global_load_dwordx4 v[216:219], v[234:235], off
	global_load_dwordx4 v[220:223], v[234:235], off offset:64
	global_load_dwordx4 v[224:227], v[234:235], off offset:512
	global_load_dwordx4 v[228:231], v[234:235], off offset:576
	s_nop 0
	v_addc_co_u32_e32 v39, vcc, 0, v167, vcc
	s_mov_b64 s[6:7], 0xb0000
	s_waitcnt vmcnt(11)
	v_pk_fma_f32 v[30:31], v[30:31], v[162:163], v[202:203]
	v_pk_fma_f32 v[28:29], v[28:29], v[164:165], v[200:201]
	global_store_dwordx4 v[38:39], v[28:31], off
	s_waitcnt vmcnt(11)
	v_pk_fma_f32 v[26:27], v[26:27], v[142:143], v[206:207]
	v_pk_fma_f32 v[24:25], v[24:25], v[160:161], v[204:205]
	global_store_dwordx4 v[36:37], v[24:27], off offset:64
	s_waitcnt vmcnt(11)
	v_pk_fma_f32 v[22:23], v[22:23], v[138:139], v[210:211]
	v_pk_fma_f32 v[20:21], v[20:21], v[140:141], v[208:209]
	global_store_dwordx4 v[36:37], v[20:23], off offset:512
	s_waitcnt vmcnt(11)
	v_pk_fma_f32 v[18:19], v[18:19], v[136:137], v[214:215]
	v_pk_fma_f32 v[16:17], v[16:17], v[134:135], v[212:213]
	global_store_dwordx4 v[36:37], v[16:19], off offset:576
	s_nop 1
	v_lshl_add_u64 v[16:17], v[166:167], 0, s[6:7]
	s_mov_b32 s6, 0xb0000
	v_add_co_u32_e32 v22, vcc, s6, v166
	s_mov_b64 s[6:7], s[42:43]
	s_nop 0
	v_addc_co_u32_e32 v23, vcc, 0, v167, vcc
	s_and_b64 vcc, exec, s[38:39]
	s_waitcnt vmcnt(7)
	v_pk_fma_f32 v[14:15], v[14:15], v[162:163], v[218:219]
	v_pk_fma_f32 v[12:13], v[12:13], v[164:165], v[216:217]
	global_store_dwordx4 v[22:23], v[12:15], off
	s_waitcnt vmcnt(7)
	v_pk_fma_f32 v[10:11], v[10:11], v[142:143], v[222:223]
	v_pk_fma_f32 v[8:9], v[8:9], v[160:161], v[220:221]
	global_store_dwordx4 v[16:17], v[8:11], off offset:64
	s_waitcnt vmcnt(7)
	v_pk_fma_f32 v[6:7], v[6:7], v[138:139], v[226:227]
	v_pk_fma_f32 v[4:5], v[4:5], v[140:141], v[224:225]
	global_store_dwordx4 v[16:17], v[4:7], off offset:512
	s_waitcnt vmcnt(7)
	v_pk_fma_f32 v[2:3], v[2:3], v[136:137], v[230:231]
	v_pk_fma_f32 v[0:1], v[0:1], v[134:135], v[228:229]
	global_store_dwordx4 v[16:17], v[0:3], off offset:576
	s_cbranch_vccnz .LBB0_1133
